# win + gemm_f32 k-loops: A fragments triple-buffered in registers, both k-steps B fragments resident, counted lgkmcnt
# speedup vs baseline: 1.0357x; 1.0301x over previous
; template <int MI, int NJ> ...
;     ...
;   for (int kt = 0; kt < nk; ++kt) {
;     const int buf = kt & 1;
;     {
;       G8STORE(buf ^ 1);
;       const u16* ga_ = (kt + 2 < nk) ? Ag + (kt + 2) * 64 : Ag + nAoff;
;       const u16* gb_ = (kt + 2 < nk) ? Bg + (kt + 2) * 64 : Bg + nBoff;
;       G8LOADP(ga_, gb_);
;     }
;     __builtin_amdgcn_sched_barrier(0);
;     __builtin_amdgcn_s_setprio(1);
;     const u16* a = ra_ + buf * AROWS * 64;
;     const u16* b = rb_ + buf * BROWS * 64;
; #pragma unroll
;     for (int ks = 0; ks < 2; ++ks) {
;       const u16* a_ = ks ? a + dsw : a;
;       const u16* b_ = ks ? b + dsw : b;
;       bf16x8 bfr[NJ];
; #pragma unroll
;       for (int j = 0; j < NJ; ++j) bfr[j] = *(const bf16x8*)(b_ + j * 16 * 64);
; #pragma unroll
;       for (int ih = 0; ih < MI / 4; ++ih) {
;         bf16x8 af[4];
; #pragma unroll
;         for (int i = 0; i < 4; ++i) af[i] = *(const bf16x8*)(a_ + (ih * 4 + i) * 16 * 64);
; #pragma unroll
;         for (int i = 0; i < 4; ++i)
; #pragma unroll
;           for (int j = 0; j < NJ; ++j) acc[ih * 4 + i][j] = mfma16(af[i], bfr[j], acc[ih * 4 + i][j]);
;       }
;     }
;     __builtin_amdgcn_s_setprio(0);
;     __builtin_amdgcn_sched_barrier(0);
;     __syncthreads();
;   }
.LBB0_470:
	s_and_b32 s38, s11, 0x4000
	s_xor_b32 s39, s38, 0x4000
	s_lshl_b32 s39, s39, 1
	s_cmp_lt_u32 s37, 14
	v_add_u32_e32 v0, s39, v185
	s_cselect_b32 s49, s21, s13
	s_cselect_b32 s48, s20, s12
	v_add_u32_e32 v191, s39, v186
	s_waitcnt vmcnt(5)
	ds_write_b128 v0, v[10:13]
	ds_write_b128 v0, v[2:5] offset:8192
	ds_write_b128 v0, v[6:9] offset:16384
	s_waitcnt vmcnt(3)
	ds_write_b128 v0, v[18:21] offset:24576
	ds_write_b128 v191, v[14:17]
	v_lshl_add_u64 v[14:15], s[48:49], 1, v[180:181]
	v_add_co_u32_e32 v2, vcc, s15, v14
	s_cselect_b32 s49, s21, s47
	s_nop 0
	v_addc_co_u32_e32 v3, vcc, 0, v15, vcc
	v_add_co_u32_e32 v6, vcc, s14, v14
	s_cselect_b32 s48, s20, s46
	s_nop 0
	v_addc_co_u32_e32 v7, vcc, 0, v15, vcc
	global_load_dwordx4 v[10:13], v[14:15], off
	v_add_co_u32_e32 v14, vcc, s54, v14
	v_lshl_add_u64 v[30:31], s[48:49], 1, v[182:183]
	s_nop 0
	v_addc_co_u32_e32 v15, vcc, 0, v15, vcc
	v_add_co_u32_e32 v22, vcc, s15, v30
	global_load_dwordx4 v[2:5], v[2:3], off
	s_nop 0
	v_addc_co_u32_e32 v23, vcc, 0, v31, vcc
	v_add_co_u32_e32 v26, vcc, s14, v30
	global_load_dwordx4 v[6:9], v[6:7], off
	s_nop 0
	v_addc_co_u32_e32 v27, vcc, 0, v31, vcc
	global_load_dwordx4 v[18:21], v[14:15], off
	s_nop 0
	global_load_dwordx4 v[14:17], v[30:31], off
	v_add_co_u32_e32 v30, vcc, s54, v30
	global_load_dwordx4 v[22:25], v[22:23], off
	s_nop 0
	v_addc_co_u32_e32 v31, vcc, 0, v31, vcc
	global_load_dwordx4 v[26:29], v[26:27], off
	s_waitcnt vmcnt(9)
	ds_write_b128 v191, v[166:169] offset:8192
	global_load_dwordx4 v[30:33], v[30:31], off
	s_waitcnt vmcnt(9)
	ds_write_b128 v191, v[170:173] offset:16384
	s_waitcnt vmcnt(8)
	ds_write_b128 v191, v[162:165] offset:24576
	s_setprio 1
	s_lshl_b32 s38, s38, 1
	v_add_u32_e32 v0, s38, v187
	v_add_u32_e32 v191, s38, v188
	ds_read_b128 v[166:169], v191
	ds_read_b128 v[162:165], v0
	ds_read_b128 v[170:173], v191 offset:2048
	ds_read_b128 v[192:195], v191 offset:4096
	ds_read_b128 v[196:199], v191 offset:6144
	ds_read_b128 v[204:207], v0 offset:2048
	ds_read_b128 v[208:211], v0 offset:4096
	v_add_u32_e32 v191, v191, v190
	s_waitcnt lgkmcnt(5)
	v_mfma_f32_16x16x32_bf16 v[158:161], v[162:165], v[166:169], v[158:161]
	s_waitcnt lgkmcnt(4)
	v_mfma_f32_16x16x32_bf16 v[154:157], v[162:165], v[170:173], v[154:157]
	s_waitcnt lgkmcnt(3)
	v_mfma_f32_16x16x32_bf16 v[150:153], v[162:165], v[192:195], v[150:153]
	s_waitcnt lgkmcnt(2)
	v_mfma_f32_16x16x32_bf16 v[146:149], v[162:165], v[196:199], v[146:149]
	ds_read_b128 v[162:165], v0 offset:6144
	s_waitcnt lgkmcnt(2)
	v_mfma_f32_16x16x32_bf16 v[142:145], v[204:207], v[166:169], v[142:145]
	v_mfma_f32_16x16x32_bf16 v[138:141], v[204:207], v[170:173], v[138:141]
	v_mfma_f32_16x16x32_bf16 v[134:137], v[204:207], v[192:195], v[134:137]
	v_mfma_f32_16x16x32_bf16 v[130:133], v[204:207], v[196:199], v[130:133]
	ds_read_b128 v[204:207], v0 offset:8192
	s_waitcnt lgkmcnt(2)
	v_mfma_f32_16x16x32_bf16 v[126:129], v[208:211], v[166:169], v[126:129]
	v_mfma_f32_16x16x32_bf16 v[122:125], v[208:211], v[170:173], v[122:125]
	v_mfma_f32_16x16x32_bf16 v[118:121], v[208:211], v[192:195], v[118:121]
	v_mfma_f32_16x16x32_bf16 v[114:117], v[208:211], v[196:199], v[114:117]
	ds_read_b128 v[208:211], v0 offset:10240
	ds_read_b128 v[212:215], v191
	ds_read_b128 v[216:219], v191 offset:2048
	s_waitcnt lgkmcnt(4)
	v_mfma_f32_16x16x32_bf16 v[110:113], v[162:165], v[166:169], v[110:113]
	v_mfma_f32_16x16x32_bf16 v[106:109], v[162:165], v[170:173], v[106:109]
	v_mfma_f32_16x16x32_bf16 v[102:105], v[162:165], v[192:195], v[102:105]
	v_mfma_f32_16x16x32_bf16 v[98:101], v[162:165], v[196:199], v[98:101]
	ds_read_b128 v[162:165], v0 offset:12288
	ds_read_b128 v[220:223], v191 offset:4096
	ds_read_b128 v[224:227], v191 offset:6144
	s_waitcnt lgkmcnt(6)
	v_mfma_f32_16x16x32_bf16 v[94:97], v[204:207], v[166:169], v[94:97]
	v_mfma_f32_16x16x32_bf16 v[90:93], v[204:207], v[170:173], v[90:93]
	v_mfma_f32_16x16x32_bf16 v[86:89], v[204:207], v[192:195], v[86:89]
	v_mfma_f32_16x16x32_bf16 v[82:85], v[204:207], v[196:199], v[82:85]
	ds_read_b128 v[204:207], v0 offset:14336
	s_waitcnt lgkmcnt(6)
	v_mfma_f32_16x16x32_bf16 v[78:81], v[208:211], v[166:169], v[78:81]
	v_mfma_f32_16x16x32_bf16 v[74:77], v[208:211], v[170:173], v[74:77]
	v_mfma_f32_16x16x32_bf16 v[70:73], v[208:211], v[192:195], v[70:73]
	v_mfma_f32_16x16x32_bf16 v[66:69], v[208:211], v[196:199], v[66:69]
	v_add_u32_e32 v0, v0, v190
	ds_read_b128 v[208:211], v0
	s_waitcnt lgkmcnt(4)
	v_mfma_f32_16x16x32_bf16 v[62:65], v[162:165], v[166:169], v[62:65]
	v_mfma_f32_16x16x32_bf16 v[58:61], v[162:165], v[170:173], v[58:61]
	v_mfma_f32_16x16x32_bf16 v[54:57], v[162:165], v[192:195], v[54:57]
	v_mfma_f32_16x16x32_bf16 v[50:53], v[162:165], v[196:199], v[50:53]
	ds_read_b128 v[162:165], v0 offset:2048
	s_waitcnt lgkmcnt(2)
	v_mfma_f32_16x16x32_bf16 v[46:49], v[204:207], v[166:169], v[46:49]
	v_mfma_f32_16x16x32_bf16 v[42:45], v[204:207], v[170:173], v[42:45]
	v_mfma_f32_16x16x32_bf16 v[38:41], v[204:207], v[192:195], v[38:41]
	v_mfma_f32_16x16x32_bf16 v[34:37], v[204:207], v[196:199], v[34:37]
	ds_read_b128 v[204:207], v0 offset:4096
	s_waitcnt lgkmcnt(2)
	v_mfma_f32_16x16x32_bf16 v[158:161], v[208:211], v[212:215], v[158:161]
	v_mfma_f32_16x16x32_bf16 v[154:157], v[208:211], v[216:219], v[154:157]
	v_mfma_f32_16x16x32_bf16 v[150:153], v[208:211], v[220:223], v[150:153]
	v_mfma_f32_16x16x32_bf16 v[146:149], v[208:211], v[224:227], v[146:149]
	ds_read_b128 v[208:211], v0 offset:6144
	s_waitcnt lgkmcnt(2)
; template <int MI, int NJ> ...
;     ...
; #pragma unroll
;     for (int ks = 0; ks < 2; ++ks) {
;       const u16* a_ = ks ? a + dsw : a;
;       const u16* b_ = ks ? b + dsw : b;
;       bf16x8 bfr[NJ];
; #pragma unroll
;       for (int j = 0; j < NJ; ++j) bfr[j] = *(const bf16x8*)(b_ + j * 16 * 64);
; #pragma unroll
;       for (int ih = 0; ih < MI / 4; ++ih) {
;         bf16x8 af[4];
; #pragma unroll
;         for (int i = 0; i < 4; ++i) af[i] = *(const bf16x8*)(a_ + (ih * 4 + i) * 16 * 64);
; #pragma unroll
;         for (int i = 0; i < 4; ++i)
; #pragma unroll
;           for (int j = 0; j < NJ; ++j) acc[ih * 4 + i][j] = mfma16(af[i], bfr[j], acc[ih * 4 + i][j]);
;       }
;     }
;     __builtin_amdgcn_s_setprio(0);
;     __builtin_amdgcn_sched_barrier(0);
;     __syncthreads();
;   }
; __device__ __forceinline__ void phase_win(const Params& p, int part, u16* smem, volatile LAS unsigned* vb_) {
;     ...
; #pragma unroll
;     for (int i = 0; i < 8; ++i)
; #pragma unroll
;       for (int j = 0; j < 4; ++j)
; #pragma unroll
;         for (int r = 0; r < 4; ++r)
;           smem[(wm * 128 + i * 16 + (lane >> 4) * 4 + r) * 264 + wn * 64 + j * 16 + (lane & 15)] = f2bf(acc[i][j][r]);
	v_mfma_f32_16x16x32_bf16 v[142:145], v[162:165], v[212:215], v[142:145]
	v_mfma_f32_16x16x32_bf16 v[138:141], v[162:165], v[216:219], v[138:141]
	v_mfma_f32_16x16x32_bf16 v[134:137], v[162:165], v[220:223], v[134:137]
	v_mfma_f32_16x16x32_bf16 v[130:133], v[162:165], v[224:227], v[130:133]
	ds_read_b128 v[162:165], v0 offset:8192
	s_waitcnt lgkmcnt(2)
	v_mfma_f32_16x16x32_bf16 v[126:129], v[204:207], v[212:215], v[126:129]
	v_mfma_f32_16x16x32_bf16 v[122:125], v[204:207], v[216:219], v[122:125]
	v_mfma_f32_16x16x32_bf16 v[118:121], v[204:207], v[220:223], v[118:121]
	v_mfma_f32_16x16x32_bf16 v[114:117], v[204:207], v[224:227], v[114:117]
	ds_read_b128 v[204:207], v0 offset:10240
	s_waitcnt lgkmcnt(2)
	v_mfma_f32_16x16x32_bf16 v[110:113], v[208:211], v[212:215], v[110:113]
	v_mfma_f32_16x16x32_bf16 v[106:109], v[208:211], v[216:219], v[106:109]
	v_mfma_f32_16x16x32_bf16 v[102:105], v[208:211], v[220:223], v[102:105]
	v_mfma_f32_16x16x32_bf16 v[98:101], v[208:211], v[224:227], v[98:101]
	ds_read_b128 v[208:211], v0 offset:12288
	s_waitcnt lgkmcnt(2)
	v_mfma_f32_16x16x32_bf16 v[94:97], v[162:165], v[212:215], v[94:97]
	v_mfma_f32_16x16x32_bf16 v[90:93], v[162:165], v[216:219], v[90:93]
	v_mfma_f32_16x16x32_bf16 v[86:89], v[162:165], v[220:223], v[86:89]
	v_mfma_f32_16x16x32_bf16 v[82:85], v[162:165], v[224:227], v[82:85]
	ds_read_b128 v[162:165], v0 offset:14336
	s_waitcnt lgkmcnt(2)
	v_mfma_f32_16x16x32_bf16 v[78:81], v[204:207], v[212:215], v[78:81]
	v_mfma_f32_16x16x32_bf16 v[74:77], v[204:207], v[216:219], v[74:77]
	v_mfma_f32_16x16x32_bf16 v[70:73], v[204:207], v[220:223], v[70:73]
	v_mfma_f32_16x16x32_bf16 v[66:69], v[204:207], v[224:227], v[66:69]
	s_waitcnt lgkmcnt(1)
	v_mfma_f32_16x16x32_bf16 v[62:65], v[208:211], v[212:215], v[62:65]
	v_mfma_f32_16x16x32_bf16 v[58:61], v[208:211], v[216:219], v[58:61]
	v_mfma_f32_16x16x32_bf16 v[54:57], v[208:211], v[220:223], v[54:57]
	v_mfma_f32_16x16x32_bf16 v[50:53], v[208:211], v[224:227], v[50:53]
	s_waitcnt lgkmcnt(0)
	v_mfma_f32_16x16x32_bf16 v[46:49], v[162:165], v[212:215], v[46:49]
	v_mfma_f32_16x16x32_bf16 v[42:45], v[162:165], v[216:219], v[42:45]
	v_mfma_f32_16x16x32_bf16 v[38:41], v[162:165], v[220:223], v[38:41]
	v_mfma_f32_16x16x32_bf16 v[34:37], v[162:165], v[224:227], v[34:37]
	s_setprio 0
	s_add_i32 s37, s37, 1
	s_add_u32 s20, s20, 64
	s_addc_u32 s21, s21, 0
	s_addk_i32 s11, 0x4000
	s_cmpk_lg_i32 s20, 0x480
	s_waitcnt vmcnt(2)
	v_mov_b64_e32 v[166:167], v[22:23]
	v_mov_b64_e32 v[168:169], v[24:25]
	s_waitcnt vmcnt(1)
	v_mov_b64_e32 v[170:171], v[26:27]
	v_mov_b64_e32 v[172:173], v[28:29]
	s_waitcnt vmcnt(0)
	v_mov_b64_e32 v[162:163], v[30:31]
	v_mov_b64_e32 v[164:165], v[32:33]
	s_barrier
	s_cbranch_scc1 .LBB0_470
	v_cvt_pk_bf16_f32 v0, v158, s0
	ds_write_b16 v189, v0
	v_cvt_pk_bf16_f32 v0, v159, s0
	ds_write_b16 v189, v0 offset:528
	v_cvt_pk_bf16_f32 v0, v160, s0
	ds_write_b16 v189, v0 offset:1056
	v_cvt_pk_bf16_f32 v0, v161, s0
	ds_write_b16 v189, v0 offset:1584
	v_cvt_pk_bf16_f32 v0, v154, s0
	ds_write_b16 v189, v0 offset:32
	v_cvt_pk_bf16_f32 v0, v155, s0
	ds_write_b16 v189, v0 offset:560
	v_cvt_pk_bf16_f32 v0, v156, s0
	ds_write_b16 v189, v0 offset:1088
	v_cvt_pk_bf16_f32 v0, v157, s0
	ds_write_b16 v189, v0 offset:1616
	v_cvt_pk_bf16_f32 v0, v150, s0
	ds_write_b16 v189, v0 offset:64
	v_cvt_pk_bf16_f32 v0, v151, s0
	ds_write_b16 v189, v0 offset:592
	v_cvt_pk_bf16_f32 v0, v152, s0
	ds_write_b16 v189, v0 offset:1120
	v_cvt_pk_bf16_f32 v0, v153, s0
	ds_write_b16 v189, v0 offset:1648
	v_cvt_pk_bf16_f32 v0, v146, s0
	ds_write_b16 v189, v0 offset:96
	v_cvt_pk_bf16_f32 v0, v147, s0
	ds_write_b16 v189, v0 offset:624
	v_cvt_pk_bf16_f32 v0, v148, s0
	ds_write_b16 v189, v0 offset:1152
	v_cvt_pk_bf16_f32 v0, v149, s0
	ds_write_b16 v189, v0 offset:1680
	v_cvt_pk_bf16_f32 v0, v142, s0
	ds_write_b16 v189, v0 offset:8448
	v_cvt_pk_bf16_f32 v0, v143, s0
	ds_write_b16 v189, v0 offset:8976
	v_cvt_pk_bf16_f32 v0, v144, s0
	ds_write_b16 v189, v0 offset:9504
	v_cvt_pk_bf16_f32 v0, v145, s0
	ds_write_b16 v189, v0 offset:10032
	v_cvt_pk_bf16_f32 v0, v138, s0
	ds_write_b16 v189, v0 offset:8480
	v_cvt_pk_bf16_f32 v0, v139, s0
	ds_write_b16 v189, v0 offset:9008
	v_cvt_pk_bf16_f32 v0, v140, s0
	ds_write_b16 v189, v0 offset:9536
	v_cvt_pk_bf16_f32 v0, v141, s0
	ds_write_b16 v189, v0 offset:10064
	v_cvt_pk_bf16_f32 v0, v134, s0
	ds_write_b16 v189, v0 offset:8512
	v_cvt_pk_bf16_f32 v0, v135, s0
	ds_write_b16 v189, v0 offset:9040
	v_cvt_pk_bf16_f32 v0, v136, s0
	ds_write_b16 v189, v0 offset:9568
	v_cvt_pk_bf16_f32 v0, v137, s0
	ds_write_b16 v189, v0 offset:10096
	v_cvt_pk_bf16_f32 v0, v130, s0
	ds_write_b16 v189, v0 offset:8544
	v_cvt_pk_bf16_f32 v0, v131, s0
	ds_write_b16 v189, v0 offset:9072
	v_cvt_pk_bf16_f32 v0, v132, s0
	ds_write_b16 v189, v0 offset:9600
	v_cvt_pk_bf16_f32 v0, v133, s0
	ds_write_b16 v189, v0 offset:10128
	v_cvt_pk_bf16_f32 v0, v126, s0
	ds_write_b16 v189, v0 offset:16896
	v_cvt_pk_bf16_f32 v0, v127, s0
	ds_write_b16 v189, v0 offset:17424
	v_cvt_pk_bf16_f32 v0, v128, s0
	ds_write_b16 v189, v0 offset:17952
	v_cvt_pk_bf16_f32 v0, v129, s0
	ds_write_b16 v189, v0 offset:18480
	v_cvt_pk_bf16_f32 v0, v122, s0
	ds_write_b16 v189, v0 offset:16928
	v_cvt_pk_bf16_f32 v0, v123, s0
	ds_write_b16 v189, v0 offset:17456
	v_cvt_pk_bf16_f32 v0, v124, s0
	ds_write_b16 v189, v0 offset:17984
	v_cvt_pk_bf16_f32 v0, v125, s0
	ds_write_b16 v189, v0 offset:18512
	v_cvt_pk_bf16_f32 v0, v118, s0
	ds_write_b16 v189, v0 offset:16960
	v_cvt_pk_bf16_f32 v0, v119, s0
	ds_write_b16 v189, v0 offset:17488
	v_cvt_pk_bf16_f32 v0, v120, s0
	ds_write_b16 v189, v0 offset:18016
	v_cvt_pk_bf16_f32 v0, v121, s0
; __device__ __forceinline__ void phase_win(const Params& p, int part, u16* smem, volatile LAS unsigned* vb_) {
;     ...
; #pragma unroll
;     for (int i = 0; i < 8; ++i)
; #pragma unroll
;       for (int j = 0; j < 4; ++j)
; #pragma unroll
;         for (int r = 0; r < 4; ++r)
;           smem[(wm * 128 + i * 16 + (lane >> 4) * 4 + r) * 264 + wn * 64 + j * 16 + (lane & 15)] = f2bf(acc[i][j][r]);
;     __syncthreads();
	ds_write_b16 v189, v0 offset:18544
	v_cvt_pk_bf16_f32 v0, v114, s0
	ds_write_b16 v189, v0 offset:16992
	v_cvt_pk_bf16_f32 v0, v115, s0
	ds_write_b16 v189, v0 offset:17520
	v_cvt_pk_bf16_f32 v0, v116, s0
	ds_write_b16 v189, v0 offset:18048
	v_cvt_pk_bf16_f32 v0, v117, s0
	ds_write_b16 v189, v0 offset:18576
	v_cvt_pk_bf16_f32 v0, v110, s0
	ds_write_b16 v189, v0 offset:25344
	v_cvt_pk_bf16_f32 v0, v111, s0
	ds_write_b16 v189, v0 offset:25872
	v_cvt_pk_bf16_f32 v0, v112, s0
	ds_write_b16 v189, v0 offset:26400
	v_cvt_pk_bf16_f32 v0, v113, s0
	ds_write_b16 v189, v0 offset:26928
	v_cvt_pk_bf16_f32 v0, v106, s0
	ds_write_b16 v189, v0 offset:25376
	v_cvt_pk_bf16_f32 v0, v107, s0
	ds_write_b16 v189, v0 offset:25904
	v_cvt_pk_bf16_f32 v0, v108, s0
	ds_write_b16 v189, v0 offset:26432
	v_cvt_pk_bf16_f32 v0, v109, s0
	ds_write_b16 v189, v0 offset:26960
	v_cvt_pk_bf16_f32 v0, v102, s0
	ds_write_b16 v189, v0 offset:25408
	v_cvt_pk_bf16_f32 v0, v103, s0
	ds_write_b16 v189, v0 offset:25936
	v_cvt_pk_bf16_f32 v0, v104, s0
	ds_write_b16 v189, v0 offset:26464
	v_cvt_pk_bf16_f32 v0, v105, s0
	ds_write_b16 v189, v0 offset:26992
	v_cvt_pk_bf16_f32 v0, v98, s0
	ds_write_b16 v189, v0 offset:25440
	v_cvt_pk_bf16_f32 v0, v99, s0
	ds_write_b16 v189, v0 offset:25968
	v_cvt_pk_bf16_f32 v0, v100, s0
	ds_write_b16 v189, v0 offset:26496
	v_cvt_pk_bf16_f32 v0, v101, s0
	ds_write_b16 v189, v0 offset:27024
	v_cvt_pk_bf16_f32 v0, v94, s0
	ds_write_b16 v189, v0 offset:33792
	v_cvt_pk_bf16_f32 v0, v95, s0
	ds_write_b16 v189, v0 offset:34320
	v_cvt_pk_bf16_f32 v0, v96, s0
	ds_write_b16 v189, v0 offset:34848
	v_cvt_pk_bf16_f32 v0, v97, s0
	ds_write_b16 v189, v0 offset:35376
	v_cvt_pk_bf16_f32 v0, v90, s0
	ds_write_b16 v189, v0 offset:33824
	v_cvt_pk_bf16_f32 v0, v91, s0
	ds_write_b16 v189, v0 offset:34352
	v_cvt_pk_bf16_f32 v0, v92, s0
	ds_write_b16 v189, v0 offset:34880
	v_cvt_pk_bf16_f32 v0, v93, s0
	ds_write_b16 v189, v0 offset:35408
	v_cvt_pk_bf16_f32 v0, v86, s0
	ds_write_b16 v189, v0 offset:33856
	v_cvt_pk_bf16_f32 v0, v87, s0
	ds_write_b16 v189, v0 offset:34384
	v_cvt_pk_bf16_f32 v0, v88, s0
	ds_write_b16 v189, v0 offset:34912
	v_cvt_pk_bf16_f32 v0, v89, s0
	ds_write_b16 v189, v0 offset:35440
	v_cvt_pk_bf16_f32 v0, v82, s0
	ds_write_b16 v189, v0 offset:33888
	v_cvt_pk_bf16_f32 v0, v83, s0
	ds_write_b16 v189, v0 offset:34416
	v_cvt_pk_bf16_f32 v0, v84, s0
	ds_write_b16 v189, v0 offset:34944
	v_cvt_pk_bf16_f32 v0, v85, s0
	ds_write_b16 v189, v0 offset:35472
	v_cvt_pk_bf16_f32 v0, v78, s0
	ds_write_b16 v189, v0 offset:42240
	v_cvt_pk_bf16_f32 v0, v79, s0
	ds_write_b16 v189, v0 offset:42768
	v_cvt_pk_bf16_f32 v0, v80, s0
	ds_write_b16 v189, v0 offset:43296
	v_cvt_pk_bf16_f32 v0, v81, s0
	ds_write_b16 v189, v0 offset:43824
	v_cvt_pk_bf16_f32 v0, v74, s0
	ds_write_b16 v189, v0 offset:42272
	v_cvt_pk_bf16_f32 v0, v75, s0
	ds_write_b16 v189, v0 offset:42800
	v_cvt_pk_bf16_f32 v0, v76, s0
	ds_write_b16 v189, v0 offset:43328
	v_cvt_pk_bf16_f32 v0, v77, s0
	ds_write_b16 v189, v0 offset:43856
	v_cvt_pk_bf16_f32 v0, v70, s0
	ds_write_b16 v189, v0 offset:42304
	v_cvt_pk_bf16_f32 v0, v71, s0
	ds_write_b16 v189, v0 offset:42832
	v_cvt_pk_bf16_f32 v0, v72, s0
	ds_write_b16 v189, v0 offset:43360
	v_cvt_pk_bf16_f32 v0, v73, s0
	ds_write_b16 v189, v0 offset:43888
	v_cvt_pk_bf16_f32 v0, v66, s0
	ds_write_b16 v189, v0 offset:42336
	v_cvt_pk_bf16_f32 v0, v67, s0
	ds_write_b16 v189, v0 offset:42864
	v_cvt_pk_bf16_f32 v0, v68, s0
	ds_write_b16 v189, v0 offset:43392
	v_cvt_pk_bf16_f32 v0, v69, s0
	ds_write_b16 v189, v0 offset:43920
	v_cvt_pk_bf16_f32 v0, v62, s0
	ds_write_b16 v189, v0 offset:50688
	v_cvt_pk_bf16_f32 v0, v63, s0
	ds_write_b16 v189, v0 offset:51216
	v_cvt_pk_bf16_f32 v0, v64, s0
	ds_write_b16 v189, v0 offset:51744
	v_cvt_pk_bf16_f32 v0, v65, s0
	ds_write_b16 v189, v0 offset:52272
	v_cvt_pk_bf16_f32 v0, v58, s0
	ds_write_b16 v189, v0 offset:50720
	v_cvt_pk_bf16_f32 v0, v59, s0
	ds_write_b16 v189, v0 offset:51248
	v_cvt_pk_bf16_f32 v0, v60, s0
	ds_write_b16 v189, v0 offset:51776
	v_cvt_pk_bf16_f32 v0, v61, s0
	ds_write_b16 v189, v0 offset:52304
	v_cvt_pk_bf16_f32 v0, v54, s0
	ds_write_b16 v189, v0 offset:50752
	v_cvt_pk_bf16_f32 v0, v55, s0
	ds_write_b16 v189, v0 offset:51280
	v_cvt_pk_bf16_f32 v0, v56, s0
	ds_write_b16 v189, v0 offset:51808
	v_cvt_pk_bf16_f32 v0, v57, s0
	ds_write_b16 v189, v0 offset:52336
	v_cvt_pk_bf16_f32 v0, v50, s0
	ds_write_b16 v189, v0 offset:50784
	v_cvt_pk_bf16_f32 v0, v51, s0
	ds_write_b16 v189, v0 offset:51312
	v_cvt_pk_bf16_f32 v0, v52, s0
	ds_write_b16 v189, v0 offset:51840
	v_cvt_pk_bf16_f32 v0, v53, s0
	ds_write_b16 v189, v0 offset:52368
	v_cvt_pk_bf16_f32 v0, v46, s0
	ds_write_b16 v189, v0 offset:59136
	v_cvt_pk_bf16_f32 v0, v47, s0
	ds_write_b16 v189, v0 offset:59664
	v_cvt_pk_bf16_f32 v0, v48, s0
	ds_write_b16 v189, v0 offset:60192
	v_cvt_pk_bf16_f32 v0, v49, s0
	ds_write_b16 v189, v0 offset:60720
	v_cvt_pk_bf16_f32 v0, v42, s0
	ds_write_b16 v189, v0 offset:59168
	v_cvt_pk_bf16_f32 v0, v43, s0
	ds_write_b16 v189, v0 offset:59696
	v_cvt_pk_bf16_f32 v0, v44, s0
	ds_write_b16 v189, v0 offset:60224
	v_cvt_pk_bf16_f32 v0, v45, s0
	ds_write_b16 v189, v0 offset:60752
	v_cvt_pk_bf16_f32 v0, v38, s0
	ds_write_b16 v189, v0 offset:59200
	v_cvt_pk_bf16_f32 v0, v39, s0
	ds_write_b16 v189, v0 offset:59728
	v_cvt_pk_bf16_f32 v0, v40, s0
	ds_write_b16 v189, v0 offset:60256
	v_cvt_pk_bf16_f32 v0, v41, s0
	ds_write_b16 v189, v0 offset:60784
	v_cvt_pk_bf16_f32 v0, v34, s0
	ds_write_b16 v189, v0 offset:59232
	v_cvt_pk_bf16_f32 v0, v35, s0
	ds_write_b16 v189, v0 offset:59760
	v_cvt_pk_bf16_f32 v0, v36, s0
	ds_write_b16 v189, v0 offset:60288
	v_cvt_pk_bf16_f32 v0, v37, s0
	v_mov_b32_e32 v43, v175
	ds_write_b16 v189, v0 offset:60816
	s_waitcnt lgkmcnt(0)
	s_barrier
; #define RTID opaque_tid()
; __device__ __forceinline__ void phase_win(const Params& p, int part, u16* smem, volatile LAS unsigned* vb_) {
;     ...
;     const int tid2 = RTID;
; #pragma unroll
;     for (int k = 0; k < 16; ++k) {
;       const int c = tid2 + 512 * k;
;       const int row = c >> 5, ch = c & 31;
;       const uint4 v = *(const uint4*)(smem + row * 264 + ch * 8);
;       u16* d_ = (ch < 16) ? dstA : dstB;
;       const int l_ = (ch < 16) ? ldA : ldB;
;       *(uint4*)(d_ + (size_t)(mt * 256 + row) * l_ + (ch & 15) * 8) = v;
;     }
;     __syncthreads();
	s_mov_b32 s38, s36
	v_and_b32_e32 v0, 31, v43
	v_lshlrev_b32_e32 v42, 4, v0
	v_cmp_gt_u32_e32 vcc, 16, v0
	v_mov_b32_e32 v0, 0x100
	s_nop 0
	v_cndmask_b32_e64 v0, v0, 0, vcc
	v_lshl_add_u64 v[34:35], s[44:45], 0, v[0:1]
	v_lshlrev_b32_e32 v0, 4, v43
	v_and_b32_e32 v0, 0xf0, v0
	v_lshl_add_u64 v[44:45], v[34:35], 0, v[0:1]
	v_ashrrev_i32_e32 v0, 5, v43
	v_mad_u64_u32 v[34:35], s[12:13], v0, s2, v[42:43]
	v_add_u32_e32 v0, s10, v0
	ds_read_b128 v[34:37], v34
	v_ashrrev_i32_e32 v38, 31, v0
	v_mul_lo_u32 v40, s0, v38
	v_mul_lo_u32 v41, s1, v0
	v_mad_u64_u32 v[38:39], s[12:13], s0, v0, 0
	v_add_u32_e32 v0, 0x200, v43
	v_add3_u32 v39, v39, v40, v41
	v_ashrrev_i32_e32 v0, 5, v0
	v_lshl_add_u64 v[46:47], v[38:39], 1, v[44:45]
	v_mad_u64_u32 v[38:39], s[12:13], v0, s2, v[42:43]
	ds_read_b128 v[38:41], v38
	v_add_u32_e32 v0, s10, v0
	s_waitcnt lgkmcnt(1)
	global_store_dwordx4 v[46:47], v[34:37], off
	s_and_b64 vcc, exec, s[42:43]
	s_nop 0
	v_ashrrev_i32_e32 v34, 31, v0
	v_mul_lo_u32 v36, s0, v34
	v_mul_lo_u32 v37, s1, v0
	v_mad_u64_u32 v[34:35], s[12:13], s0, v0, 0
	v_add3_u32 v35, v35, v36, v37
	v_add_u32_e32 v0, 0x400, v43
	v_lshl_add_u64 v[34:35], v[34:35], 1, v[44:45]
	v_ashrrev_i32_e32 v0, 5, v0
	s_waitcnt lgkmcnt(0)
	global_store_dwordx4 v[34:35], v[38:41], off
	v_mad_u64_u32 v[34:35], s[12:13], v0, s2, v[42:43]
	v_add_u32_e32 v0, s10, v0
	ds_read_b128 v[34:37], v34
	v_ashrrev_i32_e32 v38, 31, v0
	v_mul_lo_u32 v40, s0, v38
	v_mul_lo_u32 v41, s1, v0
	v_mad_u64_u32 v[38:39], s[12:13], s0, v0, 0
	v_add_u32_e32 v0, 0x600, v43
	v_add3_u32 v39, v39, v40, v41
	v_ashrrev_i32_e32 v0, 5, v0
	v_lshl_add_u64 v[46:47], v[38:39], 1, v[44:45]
	v_mad_u64_u32 v[38:39], s[12:13], v0, s2, v[42:43]
	ds_read_b128 v[38:41], v38
	v_add_u32_e32 v0, s10, v0
	s_waitcnt lgkmcnt(1)
	global_store_dwordx4 v[46:47], v[34:37], off
	s_nop 1
	v_ashrrev_i32_e32 v34, 31, v0
	v_mul_lo_u32 v36, s0, v34
	v_mul_lo_u32 v37, s1, v0
	v_mad_u64_u32 v[34:35], s[12:13], s0, v0, 0
	v_add3_u32 v35, v35, v36, v37
	v_add_u32_e32 v0, 0x800, v43
	v_lshl_add_u64 v[34:35], v[34:35], 1, v[44:45]
	v_ashrrev_i32_e32 v0, 5, v0
	s_waitcnt lgkmcnt(0)
	global_store_dwordx4 v[34:35], v[38:41], off
	v_mad_u64_u32 v[34:35], s[12:13], v0, s2, v[42:43]
	v_add_u32_e32 v0, s10, v0
	ds_read_b128 v[34:37], v34
	v_ashrrev_i32_e32 v38, 31, v0
	v_mul_lo_u32 v40, s0, v38
	v_mul_lo_u32 v41, s1, v0
	v_mad_u64_u32 v[38:39], s[12:13], s0, v0, 0
	v_add_u32_e32 v0, 0xa00, v43
	v_add3_u32 v39, v39, v40, v41
	v_ashrrev_i32_e32 v0, 5, v0
	v_lshl_add_u64 v[46:47], v[38:39], 1, v[44:45]
	v_mad_u64_u32 v[38:39], s[12:13], v0, s2, v[42:43]
	ds_read_b128 v[38:41], v38
	v_add_u32_e32 v0, s10, v0
	s_waitcnt lgkmcnt(1)
	global_store_dwordx4 v[46:47], v[34:37], off
	s_nop 1
	v_ashrrev_i32_e32 v34, 31, v0
	v_mul_lo_u32 v36, s0, v34
	v_mul_lo_u32 v37, s1, v0
	v_mad_u64_u32 v[34:35], s[12:13], s0, v0, 0
	v_add3_u32 v35, v35, v36, v37
	v_add_u32_e32 v0, 0xc00, v43
	v_lshl_add_u64 v[34:35], v[34:35], 1, v[44:45]
	v_ashrrev_i32_e32 v0, 5, v0
	s_waitcnt lgkmcnt(0)
	global_store_dwordx4 v[34:35], v[38:41], off
	v_mad_u64_u32 v[34:35], s[12:13], v0, s2, v[42:43]
	v_add_u32_e32 v0, s10, v0
	ds_read_b128 v[34:37], v34
	v_ashrrev_i32_e32 v38, 31, v0
	v_mul_lo_u32 v40, s0, v38
	v_mul_lo_u32 v41, s1, v0
	v_mad_u64_u32 v[38:39], s[12:13], s0, v0, 0
	v_add_u32_e32 v0, 0xe00, v43
	v_add3_u32 v39, v39, v40, v41
	v_ashrrev_i32_e32 v0, 5, v0
	v_lshl_add_u64 v[46:47], v[38:39], 1, v[44:45]
	v_mad_u64_u32 v[38:39], s[12:13], v0, s2, v[42:43]
	ds_read_b128 v[38:41], v38
	v_add_u32_e32 v0, s10, v0
	s_waitcnt lgkmcnt(1)
	global_store_dwordx4 v[46:47], v[34:37], off
	s_nop 1
	v_ashrrev_i32_e32 v34, 31, v0
	v_mul_lo_u32 v36, s0, v34
	v_mul_lo_u32 v37, s1, v0
	v_mad_u64_u32 v[34:35], s[12:13], s0, v0, 0
	v_add3_u32 v35, v35, v36, v37
	v_add_u32_e32 v0, 0x1000, v43
	v_lshl_add_u64 v[34:35], v[34:35], 1, v[44:45]
	v_ashrrev_i32_e32 v0, 5, v0
	s_waitcnt lgkmcnt(0)
; __device__ __forceinline__ void phase_win(const Params& p, int part, u16* smem, volatile LAS unsigned* vb_) {
;     ...
; #pragma unroll
;     for (int k = 0; k < 16; ++k) {
;       const int c = tid2 + 512 * k;
;       const int row = c >> 5, ch = c & 31;
;       const uint4 v = *(const uint4*)(smem + row * 264 + ch * 8);
;       u16* d_ = (ch < 16) ? dstA : dstB;
;       const int l_ = (ch < 16) ? ldA : ldB;
;       *(uint4*)(d_ + (size_t)(mt * 256 + row) * l_ + (ch & 15) * 8) = v;
;     }
;     __syncthreads();
;   }
	global_store_dwordx4 v[34:35], v[38:41], off
	v_mad_u64_u32 v[34:35], s[12:13], v0, s2, v[42:43]
	v_add_u32_e32 v0, s10, v0
	ds_read_b128 v[34:37], v34
	v_ashrrev_i32_e32 v38, 31, v0
	v_mul_lo_u32 v40, s0, v38
	v_mul_lo_u32 v41, s1, v0
	v_mad_u64_u32 v[38:39], s[12:13], s0, v0, 0
	v_add_u32_e32 v0, 0x1200, v43
	v_add3_u32 v39, v39, v40, v41
	v_ashrrev_i32_e32 v0, 5, v0
	v_lshl_add_u64 v[46:47], v[38:39], 1, v[44:45]
	v_mad_u64_u32 v[38:39], s[12:13], v0, s2, v[42:43]
	ds_read_b128 v[38:41], v38
	v_add_u32_e32 v0, s10, v0
	s_waitcnt lgkmcnt(1)
	global_store_dwordx4 v[46:47], v[34:37], off
	s_nop 1
	v_ashrrev_i32_e32 v34, 31, v0
	v_mul_lo_u32 v36, s0, v34
	v_mul_lo_u32 v37, s1, v0
	v_mad_u64_u32 v[34:35], s[12:13], s0, v0, 0
	v_add3_u32 v35, v35, v36, v37
	v_add_u32_e32 v0, 0x1400, v43
	v_lshl_add_u64 v[34:35], v[34:35], 1, v[44:45]
	v_ashrrev_i32_e32 v0, 5, v0
	s_waitcnt lgkmcnt(0)
	global_store_dwordx4 v[34:35], v[38:41], off
	v_mad_u64_u32 v[34:35], s[12:13], v0, s2, v[42:43]
	v_add_u32_e32 v0, s10, v0
	ds_read_b128 v[34:37], v34
	v_ashrrev_i32_e32 v38, 31, v0
	v_mul_lo_u32 v40, s0, v38
	v_mul_lo_u32 v41, s1, v0
	v_mad_u64_u32 v[38:39], s[12:13], s0, v0, 0
	v_add_u32_e32 v0, 0x1600, v43
	v_add3_u32 v39, v39, v40, v41
	v_ashrrev_i32_e32 v0, 5, v0
	v_lshl_add_u64 v[46:47], v[38:39], 1, v[44:45]
	v_mad_u64_u32 v[38:39], s[12:13], v0, s2, v[42:43]
	ds_read_b128 v[38:41], v38
	v_add_u32_e32 v0, s10, v0
	s_waitcnt lgkmcnt(1)
	global_store_dwordx4 v[46:47], v[34:37], off
	s_nop 1
	v_ashrrev_i32_e32 v34, 31, v0
	v_mul_lo_u32 v36, s0, v34
	v_mul_lo_u32 v37, s1, v0
	v_mad_u64_u32 v[34:35], s[12:13], s0, v0, 0
	v_add3_u32 v35, v35, v36, v37
	v_add_u32_e32 v0, 0x1800, v43
	v_lshl_add_u64 v[34:35], v[34:35], 1, v[44:45]
	v_ashrrev_i32_e32 v0, 5, v0
	s_waitcnt lgkmcnt(0)
	global_store_dwordx4 v[34:35], v[38:41], off
	v_mad_u64_u32 v[34:35], s[12:13], v0, s2, v[42:43]
	v_add_u32_e32 v0, s10, v0
	ds_read_b128 v[34:37], v34
	v_ashrrev_i32_e32 v38, 31, v0
	v_mul_lo_u32 v40, s0, v38
	v_mul_lo_u32 v41, s1, v0
	v_mad_u64_u32 v[38:39], s[12:13], s0, v0, 0
	v_add_u32_e32 v0, 0x1a00, v43
	v_add3_u32 v39, v39, v40, v41
	v_ashrrev_i32_e32 v0, 5, v0
	v_lshl_add_u64 v[46:47], v[38:39], 1, v[44:45]
	v_mad_u64_u32 v[38:39], s[12:13], v0, s2, v[42:43]
	ds_read_b128 v[38:41], v38
	v_add_u32_e32 v0, s10, v0
	s_waitcnt lgkmcnt(1)
	global_store_dwordx4 v[46:47], v[34:37], off
	s_nop 1
	v_ashrrev_i32_e32 v34, 31, v0
	v_mul_lo_u32 v36, s0, v34
	v_mul_lo_u32 v37, s1, v0
	v_mad_u64_u32 v[34:35], s[12:13], s0, v0, 0
	v_add3_u32 v35, v35, v36, v37
	v_add_u32_e32 v0, 0x1c00, v43
	v_lshl_add_u64 v[34:35], v[34:35], 1, v[44:45]
	v_ashrrev_i32_e32 v0, 5, v0
	s_waitcnt lgkmcnt(0)
	global_store_dwordx4 v[34:35], v[38:41], off
	v_mad_u64_u32 v[34:35], s[12:13], v0, s2, v[42:43]
	v_add_u32_e32 v0, s10, v0
	ds_read_b128 v[34:37], v34
	v_ashrrev_i32_e32 v38, 31, v0
	v_mul_lo_u32 v40, s0, v38
	v_mul_lo_u32 v41, s1, v0
	v_mad_u64_u32 v[38:39], s[12:13], s0, v0, 0
	v_add_u32_e32 v0, 0x1e00, v43
	v_add3_u32 v39, v39, v40, v41
	v_ashrrev_i32_e32 v0, 5, v0
	v_lshl_add_u64 v[46:47], v[38:39], 1, v[44:45]
	v_mad_u64_u32 v[38:39], s[12:13], v0, s2, v[42:43]
	ds_read_b128 v[38:41], v38
	v_add_u32_e32 v0, s10, v0
	s_waitcnt lgkmcnt(1)
	global_store_dwordx4 v[46:47], v[34:37], off
	s_mov_b64 s[12:13], -1
	s_nop 0
	v_ashrrev_i32_e32 v34, 31, v0
	v_mul_lo_u32 v36, s0, v34
	v_mul_lo_u32 v37, s1, v0
	v_mad_u64_u32 v[34:35], s[0:1], s0, v0, 0
	v_add3_u32 v35, v35, v36, v37
	v_lshl_add_u64 v[34:35], v[34:35], 1, v[44:45]
	s_waitcnt lgkmcnt(0)
	global_store_dwordx4 v[34:35], v[38:41], off
	s_barrier
	s_cbranch_vccz .LBB0_441

; template <int MI, int NJ> ...
;     ...
;   for (int kt = 0; kt < nk; ++kt) {
;     const int buf = kt & 1;
;     {
;       G8STORE(buf ^ 1);
;       const u16* ga_ = (kt + 2 < nk) ? Ag + (kt + 2) * 64 : Ag + nAoff;
;       const u16* gb_ = (kt + 2 < nk) ? Bg + (kt + 2) * 64 : Bg + nBoff;
;       G8LOADP(ga_, gb_);
;     }
;     __builtin_amdgcn_sched_barrier(0);
;     __builtin_amdgcn_s_setprio(1);
;     const u16* a = ra_ + buf * AROWS * 64;
;     const u16* b = rb_ + buf * BROWS * 64;
; #pragma unroll
;     for (int ks = 0; ks < 2; ++ks) {
;       const u16* a_ = ks ? a + dsw : a;
;       const u16* b_ = ks ? b + dsw : b;
;       bf16x8 bfr[NJ];
; #pragma unroll
;       for (int j = 0; j < NJ; ++j) bfr[j] = *(const bf16x8*)(b_ + j * 16 * 64);
; #pragma unroll
;       for (int ih = 0; ih < MI / 4; ++ih) {
;         bf16x8 af[4];
; #pragma unroll
;         for (int i = 0; i < 4; ++i) af[i] = *(const bf16x8*)(a_ + (ih * 4 + i) * 16 * 64);
; #pragma unroll
;         for (int i = 0; i < 4; ++i)
; #pragma unroll
;           for (int j = 0; j < NJ; ++j) acc[ih * 4 + i][j] = mfma16(af[i], bfr[j], acc[ih * 4 + i][j]);
;       }
;     }
;     __builtin_amdgcn_s_setprio(0);
;     __builtin_amdgcn_sched_barrier(0);
;     __syncthreads();
;   }
.LBB0_481:
	s_and_b32 s45, s43, 0x4000
	s_xor_b32 s46, s45, 0x4000
	s_lshl_b32 s46, s46, 1
	v_add_u32_e32 v0, s46, v185
	v_add_u32_e32 v191, s46, v186
	s_add_i32 s46, s44, 2
	s_cmp_lt_u32 s46, s21
	s_cselect_b32 s47, 0, s12
	s_cselect_b32 s46, s39, s13
	s_waitcnt vmcnt(5)
	ds_write_b128 v0, v[10:13]
	ds_write_b128 v0, v[2:5] offset:8192
	ds_write_b128 v0, v[6:9] offset:16384
	s_waitcnt vmcnt(3)
	ds_write_b128 v0, v[14:17] offset:24576
	ds_write_b128 v191, v[18:21]
	v_lshl_add_u64 v[2:3], s[46:47], 1, v[180:181]
	s_cselect_b32 s47, 0, s37
	s_cselect_b32 s46, s39, s38
	v_lshl_add_u64 v[42:43], s[46:47], 1, v[182:183]
	v_lshl_add_u64 v[6:7], v[2:3], 0, s[58:59]
	v_lshl_add_u64 v[14:15], v[6:7], 0, s[0:1]
	v_lshl_add_u64 v[62:63], v[42:43], 0, s[58:59]
	global_load_dwordx4 v[10:13], v[2:3], off
	v_lshl_add_u64 v[74:75], v[62:63], 0, s[0:1]
	global_load_dwordx4 v[2:5], v[6:7], off
	s_nop 0
	global_load_dwordx4 v[6:9], v[14:15], off
	v_lshl_add_u64 v[14:15], v[14:15], 0, s[0:1]
	global_load_dwordx4 v[14:17], v[14:15], off
	s_nop 0
	global_load_dwordx4 v[18:21], v[42:43], off
	s_waitcnt vmcnt(7)
	ds_write_b128 v191, v[170:173] offset:8192
	global_load_dwordx4 v[42:45], v[62:63], off
	s_waitcnt vmcnt(7)
	ds_write_b128 v191, v[166:169] offset:16384
	global_load_dwordx4 v[62:65], v[74:75], off
	v_lshl_add_u64 v[74:75], v[74:75], 0, s[0:1]
	global_load_dwordx4 v[74:77], v[74:75], off
	s_waitcnt vmcnt(8)
	ds_write_b128 v191, v[162:165] offset:24576
	s_setprio 1
	s_lshl_b32 s45, s45, 1
	v_add_u32_e32 v0, s45, v187
	v_add_u32_e32 v191, s45, v188
	ds_read_b128 v[166:169], v191
	ds_read_b128 v[162:165], v0
	ds_read_b128 v[170:173], v191 offset:2048
	ds_read_b128 v[192:195], v191 offset:4096
	ds_read_b128 v[196:199], v191 offset:6144
	ds_read_b128 v[204:207], v0 offset:2048
	ds_read_b128 v[208:211], v0 offset:4096
	v_add_u32_e32 v191, v191, v190
	s_waitcnt lgkmcnt(5)
	v_mfma_f32_16x16x32_bf16 v[158:161], v[162:165], v[166:169], v[158:161]
	s_waitcnt lgkmcnt(4)
	v_mfma_f32_16x16x32_bf16 v[154:157], v[162:165], v[170:173], v[154:157]
	s_waitcnt lgkmcnt(3)
	v_mfma_f32_16x16x32_bf16 v[150:153], v[162:165], v[192:195], v[150:153]
	s_waitcnt lgkmcnt(2)
	v_mfma_f32_16x16x32_bf16 v[146:149], v[162:165], v[196:199], v[146:149]
	ds_read_b128 v[162:165], v0 offset:6144
	s_waitcnt lgkmcnt(2)
	v_mfma_f32_16x16x32_bf16 v[142:145], v[204:207], v[166:169], v[142:145]
	v_mfma_f32_16x16x32_bf16 v[138:141], v[204:207], v[170:173], v[138:141]
	v_mfma_f32_16x16x32_bf16 v[134:137], v[204:207], v[192:195], v[134:137]
	v_mfma_f32_16x16x32_bf16 v[130:133], v[204:207], v[196:199], v[130:133]
	ds_read_b128 v[204:207], v0 offset:8192
	s_waitcnt lgkmcnt(2)
	v_mfma_f32_16x16x32_bf16 v[126:129], v[208:211], v[166:169], v[126:129]
	v_mfma_f32_16x16x32_bf16 v[122:125], v[208:211], v[170:173], v[122:125]
	v_mfma_f32_16x16x32_bf16 v[118:121], v[208:211], v[192:195], v[118:121]
	v_mfma_f32_16x16x32_bf16 v[114:117], v[208:211], v[196:199], v[114:117]
	ds_read_b128 v[208:211], v0 offset:10240
	ds_read_b128 v[212:215], v191
	ds_read_b128 v[216:219], v191 offset:2048
	s_waitcnt lgkmcnt(4)
	v_mfma_f32_16x16x32_bf16 v[110:113], v[162:165], v[166:169], v[110:113]
	v_mfma_f32_16x16x32_bf16 v[106:109], v[162:165], v[170:173], v[106:109]
	v_mfma_f32_16x16x32_bf16 v[102:105], v[162:165], v[192:195], v[102:105]
	v_mfma_f32_16x16x32_bf16 v[98:101], v[162:165], v[196:199], v[98:101]
	ds_read_b128 v[162:165], v0 offset:12288
	ds_read_b128 v[220:223], v191 offset:4096
	ds_read_b128 v[224:227], v191 offset:6144
	s_waitcnt lgkmcnt(6)
	v_mfma_f32_16x16x32_bf16 v[94:97], v[204:207], v[166:169], v[94:97]
	v_mfma_f32_16x16x32_bf16 v[90:93], v[204:207], v[170:173], v[90:93]
	v_mfma_f32_16x16x32_bf16 v[86:89], v[204:207], v[192:195], v[86:89]
	v_mfma_f32_16x16x32_bf16 v[82:85], v[204:207], v[196:199], v[82:85]
	ds_read_b128 v[204:207], v0 offset:14336
	s_waitcnt lgkmcnt(6)
	v_mfma_f32_16x16x32_bf16 v[78:81], v[208:211], v[166:169], v[78:81]
	v_mfma_f32_16x16x32_bf16 v[70:73], v[208:211], v[170:173], v[70:73]
	v_mfma_f32_16x16x32_bf16 v[66:69], v[208:211], v[192:195], v[66:69]
	v_mfma_f32_16x16x32_bf16 v[58:61], v[208:211], v[196:199], v[58:61]
	v_add_u32_e32 v0, v0, v190
	ds_read_b128 v[208:211], v0
	s_waitcnt lgkmcnt(4)
	v_mfma_f32_16x16x32_bf16 v[54:57], v[162:165], v[166:169], v[54:57]
	v_mfma_f32_16x16x32_bf16 v[50:53], v[162:165], v[170:173], v[50:53]
	v_mfma_f32_16x16x32_bf16 v[46:49], v[162:165], v[192:195], v[46:49]
	v_mfma_f32_16x16x32_bf16 v[38:41], v[162:165], v[196:199], v[38:41]
	ds_read_b128 v[162:165], v0 offset:2048
	s_waitcnt lgkmcnt(2)
	v_mfma_f32_16x16x32_bf16 v[34:37], v[204:207], v[166:169], v[34:37]
	v_mfma_f32_16x16x32_bf16 v[30:33], v[204:207], v[170:173], v[30:33]
	v_mfma_f32_16x16x32_bf16 v[26:29], v[204:207], v[192:195], v[26:29]
	v_mfma_f32_16x16x32_bf16 v[22:25], v[204:207], v[196:199], v[22:25]
	ds_read_b128 v[204:207], v0 offset:4096
	s_waitcnt lgkmcnt(2)
	v_mfma_f32_16x16x32_bf16 v[158:161], v[208:211], v[212:215], v[158:161]
	v_mfma_f32_16x16x32_bf16 v[154:157], v[208:211], v[216:219], v[154:157]
	v_mfma_f32_16x16x32_bf16 v[150:153], v[208:211], v[220:223], v[150:153]
	v_mfma_f32_16x16x32_bf16 v[146:149], v[208:211], v[224:227], v[146:149]
	ds_read_b128 v[208:211], v0 offset:6144
	s_waitcnt lgkmcnt(2)
	v_mfma_f32_16x16x32_bf16 v[142:145], v[162:165], v[212:215], v[142:145]
	v_mfma_f32_16x16x32_bf16 v[138:141], v[162:165], v[216:219], v[138:141]
	v_mfma_f32_16x16x32_bf16 v[134:137], v[162:165], v[220:223], v[134:137]
	v_mfma_f32_16x16x32_bf16 v[130:133], v[162:165], v[224:227], v[130:133]
	ds_read_b128 v[162:165], v0 offset:8192
	s_waitcnt lgkmcnt(2)
; template <int MI, int NJ> ...
;     ...
; #pragma unroll
;     for (int ks = 0; ks < 2; ++ks) {
;       const u16* a_ = ks ? a + dsw : a;
;       const u16* b_ = ks ? b + dsw : b;
;       bf16x8 bfr[NJ];
; #pragma unroll
;       for (int j = 0; j < NJ; ++j) bfr[j] = *(const bf16x8*)(b_ + j * 16 * 64);
; #pragma unroll
;       for (int ih = 0; ih < MI / 4; ++ih) {
;         bf16x8 af[4];
; #pragma unroll
;         for (int i = 0; i < 4; ++i) af[i] = *(const bf16x8*)(a_ + (ih * 4 + i) * 16 * 64);
; #pragma unroll
;         for (int i = 0; i < 4; ++i)
; #pragma unroll
;           for (int j = 0; j < NJ; ++j) acc[ih * 4 + i][j] = mfma16(af[i], bfr[j], acc[ih * 4 + i][j]);
;       }
;     }
;     __builtin_amdgcn_s_setprio(0);
;     __builtin_amdgcn_sched_barrier(0);
;     __syncthreads();
;   }
; __device__ __forceinline__ void phase_gemm_f32(const u16* A, const u16* Bt, int K, u16* out, u16* smem,
;                                                volatile LAS unsigned* vb_) {
;     ...
; #pragma unroll
;     for (int i = 0; i < 8; ++i)
; #pragma unroll
;       for (int j = 0; j < 4; ++j)
; #pragma unroll
;         for (int r = 0; r < 4; ++r)
;           smem[(wm * 128 + i * 16 + (lane >> 4) * 4 + r) * 264 + wn * 64 + j * 16 + (lane & 15)] = f2bf(acc[i][j][r]);
	v_mfma_f32_16x16x32_bf16 v[126:129], v[204:207], v[212:215], v[126:129]
	v_mfma_f32_16x16x32_bf16 v[122:125], v[204:207], v[216:219], v[122:125]
	v_mfma_f32_16x16x32_bf16 v[118:121], v[204:207], v[220:223], v[118:121]
	v_mfma_f32_16x16x32_bf16 v[114:117], v[204:207], v[224:227], v[114:117]
	ds_read_b128 v[204:207], v0 offset:10240
	s_waitcnt lgkmcnt(2)
	v_mfma_f32_16x16x32_bf16 v[110:113], v[208:211], v[212:215], v[110:113]
	v_mfma_f32_16x16x32_bf16 v[106:109], v[208:211], v[216:219], v[106:109]
	v_mfma_f32_16x16x32_bf16 v[102:105], v[208:211], v[220:223], v[102:105]
	v_mfma_f32_16x16x32_bf16 v[98:101], v[208:211], v[224:227], v[98:101]
	ds_read_b128 v[208:211], v0 offset:12288
	s_waitcnt lgkmcnt(2)
	v_mfma_f32_16x16x32_bf16 v[94:97], v[162:165], v[212:215], v[94:97]
	v_mfma_f32_16x16x32_bf16 v[90:93], v[162:165], v[216:219], v[90:93]
	v_mfma_f32_16x16x32_bf16 v[86:89], v[162:165], v[220:223], v[86:89]
	v_mfma_f32_16x16x32_bf16 v[82:85], v[162:165], v[224:227], v[82:85]
	ds_read_b128 v[162:165], v0 offset:14336
	s_waitcnt lgkmcnt(2)
	v_mfma_f32_16x16x32_bf16 v[78:81], v[204:207], v[212:215], v[78:81]
	v_mfma_f32_16x16x32_bf16 v[70:73], v[204:207], v[216:219], v[70:73]
	v_mfma_f32_16x16x32_bf16 v[66:69], v[204:207], v[220:223], v[66:69]
	v_mfma_f32_16x16x32_bf16 v[58:61], v[204:207], v[224:227], v[58:61]
	s_waitcnt lgkmcnt(1)
	v_mfma_f32_16x16x32_bf16 v[54:57], v[208:211], v[212:215], v[54:57]
	v_mfma_f32_16x16x32_bf16 v[50:53], v[208:211], v[216:219], v[50:53]
	v_mfma_f32_16x16x32_bf16 v[46:49], v[208:211], v[220:223], v[46:49]
	v_mfma_f32_16x16x32_bf16 v[38:41], v[208:211], v[224:227], v[38:41]
	s_waitcnt lgkmcnt(0)
	v_mfma_f32_16x16x32_bf16 v[34:37], v[162:165], v[212:215], v[34:37]
	v_mfma_f32_16x16x32_bf16 v[30:33], v[162:165], v[216:219], v[30:33]
	v_mfma_f32_16x16x32_bf16 v[26:29], v[162:165], v[220:223], v[26:29]
	v_mfma_f32_16x16x32_bf16 v[22:25], v[162:165], v[224:227], v[22:25]
	s_setprio 0
	s_add_i32 s44, s44, 1
	s_add_i32 s39, s39, 64
	s_addk_i32 s43, 0x4000
	s_cmp_lg_u32 s21, s44
	s_waitcnt vmcnt(2)
	v_mov_b64_e32 v[170:171], v[42:43]
	v_mov_b64_e32 v[172:173], v[44:45]
	s_waitcnt vmcnt(1)
	v_mov_b64_e32 v[166:167], v[62:63]
	v_mov_b64_e32 v[168:169], v[64:65]
	s_waitcnt vmcnt(0)
	v_mov_b64_e32 v[162:163], v[74:75]
	v_mov_b64_e32 v[164:165], v[76:77]
	s_barrier
	s_cbranch_scc1 .LBB0_481
	v_cvt_pk_bf16_f32 v0, v158, s0
	ds_write_b16 v189, v0
	v_cvt_pk_bf16_f32 v0, v159, s0
	ds_write_b16 v189, v0 offset:528
	v_cvt_pk_bf16_f32 v0, v160, s0
	ds_write_b16 v189, v0 offset:1056
	v_cvt_pk_bf16_f32 v0, v161, s0
	ds_write_b16 v189, v0 offset:1584
	v_cvt_pk_bf16_f32 v0, v154, s0
	ds_write_b16 v189, v0 offset:32
	v_cvt_pk_bf16_f32 v0, v155, s0
	ds_write_b16 v189, v0 offset:560
	v_cvt_pk_bf16_f32 v0, v156, s0
	ds_write_b16 v189, v0 offset:1088
	v_cvt_pk_bf16_f32 v0, v157, s0
	ds_write_b16 v189, v0 offset:1616
	v_cvt_pk_bf16_f32 v0, v150, s0
	ds_write_b16 v189, v0 offset:64
	v_cvt_pk_bf16_f32 v0, v151, s0
	ds_write_b16 v189, v0 offset:592
	v_cvt_pk_bf16_f32 v0, v152, s0
	ds_write_b16 v189, v0 offset:1120
	v_cvt_pk_bf16_f32 v0, v153, s0
	ds_write_b16 v189, v0 offset:1648
	v_cvt_pk_bf16_f32 v0, v146, s0
	ds_write_b16 v189, v0 offset:96
	v_cvt_pk_bf16_f32 v0, v147, s0
	ds_write_b16 v189, v0 offset:624
	v_cvt_pk_bf16_f32 v0, v148, s0
	ds_write_b16 v189, v0 offset:1152
	v_cvt_pk_bf16_f32 v0, v149, s0
	ds_write_b16 v189, v0 offset:1680
	v_cvt_pk_bf16_f32 v0, v142, s0
	ds_write_b16 v189, v0 offset:8448
	v_cvt_pk_bf16_f32 v0, v143, s0
	ds_write_b16 v189, v0 offset:8976
	v_cvt_pk_bf16_f32 v0, v144, s0
	ds_write_b16 v189, v0 offset:9504
	v_cvt_pk_bf16_f32 v0, v145, s0
	ds_write_b16 v189, v0 offset:10032
	v_cvt_pk_bf16_f32 v0, v138, s0
	ds_write_b16 v189, v0 offset:8480
	v_cvt_pk_bf16_f32 v0, v139, s0
	ds_write_b16 v189, v0 offset:9008
	v_cvt_pk_bf16_f32 v0, v140, s0
	ds_write_b16 v189, v0 offset:9536
	v_cvt_pk_bf16_f32 v0, v141, s0
	ds_write_b16 v189, v0 offset:10064
	v_cvt_pk_bf16_f32 v0, v134, s0
	ds_write_b16 v189, v0 offset:8512
	v_cvt_pk_bf16_f32 v0, v135, s0
	ds_write_b16 v189, v0 offset:9040
	v_cvt_pk_bf16_f32 v0, v136, s0
	ds_write_b16 v189, v0 offset:9568
	v_cvt_pk_bf16_f32 v0, v137, s0
	ds_write_b16 v189, v0 offset:10096
	v_cvt_pk_bf16_f32 v0, v130, s0
	ds_write_b16 v189, v0 offset:8544
	v_cvt_pk_bf16_f32 v0, v131, s0
	ds_write_b16 v189, v0 offset:9072
	v_cvt_pk_bf16_f32 v0, v132, s0
	ds_write_b16 v189, v0 offset:9600
	v_cvt_pk_bf16_f32 v0, v133, s0
	ds_write_b16 v189, v0 offset:10128
	v_cvt_pk_bf16_f32 v0, v126, s0
	ds_write_b16 v189, v0 offset:16896
	v_cvt_pk_bf16_f32 v0, v127, s0
	ds_write_b16 v189, v0 offset:17424
	v_cvt_pk_bf16_f32 v0, v128, s0
	ds_write_b16 v189, v0 offset:17952
	v_cvt_pk_bf16_f32 v0, v129, s0
	ds_write_b16 v189, v0 offset:18480
	v_cvt_pk_bf16_f32 v0, v122, s0
	ds_write_b16 v189, v0 offset:16928
	v_cvt_pk_bf16_f32 v0, v123, s0
	ds_write_b16 v189, v0 offset:17456
	v_cvt_pk_bf16_f32 v0, v124, s0
	ds_write_b16 v189, v0 offset:17984
	v_cvt_pk_bf16_f32 v0, v125, s0
	ds_write_b16 v189, v0 offset:18512
	v_cvt_pk_bf16_f32 v0, v118, s0
	ds_write_b16 v189, v0 offset:16960
	v_cvt_pk_bf16_f32 v0, v119, s0
	ds_write_b16 v189, v0 offset:17488
	v_cvt_pk_bf16_f32 v0, v120, s0
	ds_write_b16 v189, v0 offset:18016
	v_cvt_pk_bf16_f32 v0, v121, s0
	ds_write_b16 v189, v0 offset:18544
	v_cvt_pk_bf16_f32 v0, v114, s0
	ds_write_b16 v189, v0 offset:16992
	v_cvt_pk_bf16_f32 v0, v115, s0
	ds_write_b16 v189, v0 offset:17520
	v_cvt_pk_bf16_f32 v0, v116, s0
	ds_write_b16 v189, v0 offset:18048
	v_cvt_pk_bf16_f32 v0, v117, s0
	ds_write_b16 v189, v0 offset:18576
	v_cvt_pk_bf16_f32 v0, v110, s0
	ds_write_b16 v189, v0 offset:25344
; __device__ __forceinline__ void phase_gemm_f32(const u16* A, const u16* Bt, int K, u16* out, u16* smem,
;                                                volatile LAS unsigned* vb_) {
;     ...
; #pragma unroll
;     for (int i = 0; i < 8; ++i)
; #pragma unroll
;       for (int j = 0; j < 4; ++j)
; #pragma unroll
;         for (int r = 0; r < 4; ++r)
;           smem[(wm * 128 + i * 16 + (lane >> 4) * 4 + r) * 264 + wn * 64 + j * 16 + (lane & 15)] = f2bf(acc[i][j][r]);
;     __syncthreads();
	v_cvt_pk_bf16_f32 v0, v111, s0
	ds_write_b16 v189, v0 offset:25872
	v_cvt_pk_bf16_f32 v0, v112, s0
	ds_write_b16 v189, v0 offset:26400
	v_cvt_pk_bf16_f32 v0, v113, s0
	ds_write_b16 v189, v0 offset:26928
	v_cvt_pk_bf16_f32 v0, v106, s0
	ds_write_b16 v189, v0 offset:25376
	v_cvt_pk_bf16_f32 v0, v107, s0
	ds_write_b16 v189, v0 offset:25904
	v_cvt_pk_bf16_f32 v0, v108, s0
	ds_write_b16 v189, v0 offset:26432
	v_cvt_pk_bf16_f32 v0, v109, s0
	ds_write_b16 v189, v0 offset:26960
	v_cvt_pk_bf16_f32 v0, v102, s0
	ds_write_b16 v189, v0 offset:25408
	v_cvt_pk_bf16_f32 v0, v103, s0
	ds_write_b16 v189, v0 offset:25936
	v_cvt_pk_bf16_f32 v0, v104, s0
	ds_write_b16 v189, v0 offset:26464
	v_cvt_pk_bf16_f32 v0, v105, s0
	ds_write_b16 v189, v0 offset:26992
	v_cvt_pk_bf16_f32 v0, v98, s0
	ds_write_b16 v189, v0 offset:25440
	v_cvt_pk_bf16_f32 v0, v99, s0
	ds_write_b16 v189, v0 offset:25968
	v_cvt_pk_bf16_f32 v0, v100, s0
	ds_write_b16 v189, v0 offset:26496
	v_cvt_pk_bf16_f32 v0, v101, s0
	ds_write_b16 v189, v0 offset:27024
	v_cvt_pk_bf16_f32 v0, v94, s0
	ds_write_b16 v189, v0 offset:33792
	v_cvt_pk_bf16_f32 v0, v95, s0
	ds_write_b16 v189, v0 offset:34320
	v_cvt_pk_bf16_f32 v0, v96, s0
	ds_write_b16 v189, v0 offset:34848
	v_cvt_pk_bf16_f32 v0, v97, s0
	ds_write_b16 v189, v0 offset:35376
	v_cvt_pk_bf16_f32 v0, v90, s0
	ds_write_b16 v189, v0 offset:33824
	v_cvt_pk_bf16_f32 v0, v91, s0
	ds_write_b16 v189, v0 offset:34352
	v_cvt_pk_bf16_f32 v0, v92, s0
	ds_write_b16 v189, v0 offset:34880
	v_cvt_pk_bf16_f32 v0, v93, s0
	ds_write_b16 v189, v0 offset:35408
	v_cvt_pk_bf16_f32 v0, v86, s0
	ds_write_b16 v189, v0 offset:33856
	v_cvt_pk_bf16_f32 v0, v87, s0
	ds_write_b16 v189, v0 offset:34384
	v_cvt_pk_bf16_f32 v0, v88, s0
	ds_write_b16 v189, v0 offset:34912
	v_cvt_pk_bf16_f32 v0, v89, s0
	ds_write_b16 v189, v0 offset:35440
	v_cvt_pk_bf16_f32 v0, v82, s0
	ds_write_b16 v189, v0 offset:33888
	v_cvt_pk_bf16_f32 v0, v83, s0
	ds_write_b16 v189, v0 offset:34416
	v_cvt_pk_bf16_f32 v0, v84, s0
	ds_write_b16 v189, v0 offset:34944
	v_cvt_pk_bf16_f32 v0, v85, s0
	ds_write_b16 v189, v0 offset:35472
	v_cvt_pk_bf16_f32 v0, v78, s0
	ds_write_b16 v189, v0 offset:42240
	v_cvt_pk_bf16_f32 v0, v79, s0
	ds_write_b16 v189, v0 offset:42768
	v_cvt_pk_bf16_f32 v0, v80, s0
	ds_write_b16 v189, v0 offset:43296
	v_cvt_pk_bf16_f32 v0, v81, s0
	ds_write_b16 v189, v0 offset:43824
	v_cvt_pk_bf16_f32 v0, v70, s0
	ds_write_b16 v189, v0 offset:42272
	v_cvt_pk_bf16_f32 v0, v71, s0
	ds_write_b16 v189, v0 offset:42800
	v_cvt_pk_bf16_f32 v0, v72, s0
	ds_write_b16 v189, v0 offset:43328
	v_cvt_pk_bf16_f32 v0, v73, s0
	ds_write_b16 v189, v0 offset:43856
	v_cvt_pk_bf16_f32 v0, v66, s0
	ds_write_b16 v189, v0 offset:42304
	v_cvt_pk_bf16_f32 v0, v67, s0
	ds_write_b16 v189, v0 offset:42832
	v_cvt_pk_bf16_f32 v0, v68, s0
	ds_write_b16 v189, v0 offset:43360
	v_cvt_pk_bf16_f32 v0, v69, s0
	ds_write_b16 v189, v0 offset:43888
	v_cvt_pk_bf16_f32 v0, v58, s0
	ds_write_b16 v189, v0 offset:42336
	v_cvt_pk_bf16_f32 v0, v59, s0
	ds_write_b16 v189, v0 offset:42864
	v_cvt_pk_bf16_f32 v0, v60, s0
	ds_write_b16 v189, v0 offset:43392
	v_cvt_pk_bf16_f32 v0, v61, s0
	ds_write_b16 v189, v0 offset:43920
	v_cvt_pk_bf16_f32 v0, v54, s0
	ds_write_b16 v189, v0 offset:50688
	v_cvt_pk_bf16_f32 v0, v55, s0
	ds_write_b16 v189, v0 offset:51216
	v_cvt_pk_bf16_f32 v0, v56, s0
	ds_write_b16 v189, v0 offset:51744
	v_cvt_pk_bf16_f32 v0, v57, s0
	ds_write_b16 v189, v0 offset:52272
	v_cvt_pk_bf16_f32 v0, v50, s0
	ds_write_b16 v189, v0 offset:50720
	v_cvt_pk_bf16_f32 v0, v51, s0
	ds_write_b16 v189, v0 offset:51248
	v_cvt_pk_bf16_f32 v0, v52, s0
	ds_write_b16 v189, v0 offset:51776
	v_cvt_pk_bf16_f32 v0, v53, s0
	ds_write_b16 v189, v0 offset:52304
	v_cvt_pk_bf16_f32 v0, v46, s0
	ds_write_b16 v189, v0 offset:50752
	v_cvt_pk_bf16_f32 v0, v47, s0
	ds_write_b16 v189, v0 offset:51280
	v_cvt_pk_bf16_f32 v0, v48, s0
	ds_write_b16 v189, v0 offset:51808
	v_cvt_pk_bf16_f32 v0, v49, s0
	ds_write_b16 v189, v0 offset:52336
	v_cvt_pk_bf16_f32 v0, v38, s0
	ds_write_b16 v189, v0 offset:50784
	v_cvt_pk_bf16_f32 v0, v39, s0
	ds_write_b16 v189, v0 offset:51312
	v_cvt_pk_bf16_f32 v0, v40, s0
	ds_write_b16 v189, v0 offset:51840
	v_cvt_pk_bf16_f32 v0, v41, s0
	ds_write_b16 v189, v0 offset:52368
	v_cvt_pk_bf16_f32 v0, v34, s0
	ds_write_b16 v189, v0 offset:59136
	v_cvt_pk_bf16_f32 v0, v35, s0
	ds_write_b16 v189, v0 offset:59664
	v_cvt_pk_bf16_f32 v0, v36, s0
	ds_write_b16 v189, v0 offset:60192
	v_cvt_pk_bf16_f32 v0, v37, s0
	ds_write_b16 v189, v0 offset:60720
	v_cvt_pk_bf16_f32 v0, v30, s0
	ds_write_b16 v189, v0 offset:59168
	v_cvt_pk_bf16_f32 v0, v31, s0
	ds_write_b16 v189, v0 offset:59696
	v_cvt_pk_bf16_f32 v0, v32, s0
	ds_write_b16 v189, v0 offset:60224
	v_cvt_pk_bf16_f32 v0, v33, s0
	ds_write_b16 v189, v0 offset:60752
	v_cvt_pk_bf16_f32 v0, v26, s0
	ds_write_b16 v189, v0 offset:59200
	v_cvt_pk_bf16_f32 v0, v27, s0
	ds_write_b16 v189, v0 offset:59728
	v_cvt_pk_bf16_f32 v0, v28, s0
	ds_write_b16 v189, v0 offset:60256
	v_cvt_pk_bf16_f32 v0, v29, s0
	ds_write_b16 v189, v0 offset:60784
	v_cvt_pk_bf16_f32 v0, v22, s0
	ds_write_b16 v189, v0 offset:59232
	v_cvt_pk_bf16_f32 v0, v23, s0
	ds_write_b16 v189, v0 offset:59760
	v_cvt_pk_bf16_f32 v0, v24, s0
	s_ashr_i32 s43, s42, 31
	ds_write_b16 v189, v0 offset:60288
	v_cvt_pk_bf16_f32 v0, v25, s0
	v_mov_b32_e32 v34, v175
	s_lshl_b64 s[12:13], s[42:43], 1
	ds_write_b16 v189, v0 offset:60816
	s_waitcnt lgkmcnt(0)
	s_barrier
; #define RTID opaque_tid()
; __device__ __forceinline__ void phase_gemm_f32(const u16* A, const u16* Bt, int K, u16* out, u16* smem,
;                                                volatile LAS unsigned* vb_) {
;     ...
;     const int tid2 = RTID;
; #pragma unroll
;     for (int k = 0; k < 16; ++k) {
;       const int c = tid2 + 512 * k;
;       const int row = c >> 5, ch = c & 31;
;       const uint4 v = *(const uint4*)(smem + row * 264 + ch * 8);
;       *(uint4*)(out + (size_t)(mt * 256 + row) * 1024 + nt * 256 + ch * 8) = v;
;     }
;     __syncthreads();
;   }
	s_add_u32 s12, s11, s12
	v_lshlrev_b32_e32 v0, 4, v34
	v_and_b32_e32 v0, 0x1f0, v0
	s_addc_u32 s13, s20, s13
	v_ashrrev_i32_e32 v26, 5, v34
	v_lshl_add_u64 v[30:31], s[12:13], 0, v[0:1]
	v_mad_u64_u32 v[22:23], s[12:13], v26, s2, v[0:1]
	v_add_u32_e32 v26, s23, v26
	v_ashrrev_i32_e32 v27, 31, v26
	ds_read_b128 v[22:25], v22
	v_lshlrev_b64 v[26:27], 11, v[26:27]
	v_lshl_add_u64 v[32:33], v[30:31], 0, v[26:27]
	v_add_u32_e32 v26, 0x200, v34
	v_ashrrev_i32_e32 v35, 5, v26
	v_mad_u64_u32 v[26:27], s[12:13], v35, s2, v[0:1]
	ds_read_b128 v[26:29], v26
	s_waitcnt lgkmcnt(1)
	global_store_dwordx4 v[32:33], v[22:25], off
	s_and_b64 vcc, exec, s[40:41]
	s_mov_b32 s37, s36
	v_add_u32_e32 v22, s23, v35
	v_ashrrev_i32_e32 v23, 31, v22
	v_lshlrev_b64 v[22:23], 11, v[22:23]
	v_lshl_add_u64 v[22:23], v[30:31], 0, v[22:23]
	s_waitcnt lgkmcnt(0)
	global_store_dwordx4 v[22:23], v[26:29], off
	v_add_u32_e32 v22, 0x400, v34
	s_nop 0
	v_ashrrev_i32_e32 v26, 5, v22
	v_mad_u64_u32 v[22:23], s[12:13], v26, s2, v[0:1]
	v_add_u32_e32 v26, s23, v26
	v_ashrrev_i32_e32 v27, 31, v26
	ds_read_b128 v[22:25], v22
	v_lshlrev_b64 v[26:27], 11, v[26:27]
	v_lshl_add_u64 v[32:33], v[30:31], 0, v[26:27]
	v_add_u32_e32 v26, 0x600, v34
	v_ashrrev_i32_e32 v35, 5, v26
	v_mad_u64_u32 v[26:27], s[12:13], v35, s2, v[0:1]
	ds_read_b128 v[26:29], v26
	s_waitcnt lgkmcnt(1)
	global_store_dwordx4 v[32:33], v[22:25], off
	s_nop 1
	v_add_u32_e32 v22, s23, v35
	v_ashrrev_i32_e32 v23, 31, v22
	v_lshlrev_b64 v[22:23], 11, v[22:23]
	v_lshl_add_u64 v[22:23], v[30:31], 0, v[22:23]
	s_waitcnt lgkmcnt(0)
	global_store_dwordx4 v[22:23], v[26:29], off
	v_add_u32_e32 v22, 0x800, v34
	s_nop 0
	v_ashrrev_i32_e32 v26, 5, v22
	v_mad_u64_u32 v[22:23], s[12:13], v26, s2, v[0:1]
	v_add_u32_e32 v26, s23, v26
	v_ashrrev_i32_e32 v27, 31, v26
	ds_read_b128 v[22:25], v22
	v_lshlrev_b64 v[26:27], 11, v[26:27]
	v_lshl_add_u64 v[32:33], v[30:31], 0, v[26:27]
	v_add_u32_e32 v26, 0xa00, v34
	v_ashrrev_i32_e32 v35, 5, v26
	v_mad_u64_u32 v[26:27], s[12:13], v35, s2, v[0:1]
	ds_read_b128 v[26:29], v26
	s_waitcnt lgkmcnt(1)
	global_store_dwordx4 v[32:33], v[22:25], off
	s_nop 1
	v_add_u32_e32 v22, s23, v35
	v_ashrrev_i32_e32 v23, 31, v22
	v_lshlrev_b64 v[22:23], 11, v[22:23]
	v_lshl_add_u64 v[22:23], v[30:31], 0, v[22:23]
	s_waitcnt lgkmcnt(0)
	global_store_dwordx4 v[22:23], v[26:29], off
	v_add_u32_e32 v22, 0xc00, v34
	s_nop 0
	v_ashrrev_i32_e32 v26, 5, v22
	v_mad_u64_u32 v[22:23], s[12:13], v26, s2, v[0:1]
	v_add_u32_e32 v26, s23, v26
	v_ashrrev_i32_e32 v27, 31, v26
	ds_read_b128 v[22:25], v22
	v_lshlrev_b64 v[26:27], 11, v[26:27]
	v_lshl_add_u64 v[32:33], v[30:31], 0, v[26:27]
	v_add_u32_e32 v26, 0xe00, v34
	v_ashrrev_i32_e32 v35, 5, v26
	v_mad_u64_u32 v[26:27], s[12:13], v35, s2, v[0:1]
	ds_read_b128 v[26:29], v26
	s_waitcnt lgkmcnt(1)
	global_store_dwordx4 v[32:33], v[22:25], off
	s_nop 1
	v_add_u32_e32 v22, s23, v35
	v_ashrrev_i32_e32 v23, 31, v22
	v_lshlrev_b64 v[22:23], 11, v[22:23]
	v_lshl_add_u64 v[22:23], v[30:31], 0, v[22:23]
	s_waitcnt lgkmcnt(0)
	global_store_dwordx4 v[22:23], v[26:29], off
	v_add_u32_e32 v22, 0x1000, v34
	s_nop 0
	v_ashrrev_i32_e32 v26, 5, v22
	v_mad_u64_u32 v[22:23], s[12:13], v26, s2, v[0:1]
	v_add_u32_e32 v26, s23, v26
	v_ashrrev_i32_e32 v27, 31, v26
	ds_read_b128 v[22:25], v22
	v_lshlrev_b64 v[26:27], 11, v[26:27]
	v_lshl_add_u64 v[32:33], v[30:31], 0, v[26:27]
	v_add_u32_e32 v26, 0x1200, v34
	v_ashrrev_i32_e32 v35, 5, v26
	v_mad_u64_u32 v[26:27], s[12:13], v35, s2, v[0:1]
	ds_read_b128 v[26:29], v26
	s_waitcnt lgkmcnt(1)
	global_store_dwordx4 v[32:33], v[22:25], off
	s_nop 1
	v_add_u32_e32 v22, s23, v35
	v_ashrrev_i32_e32 v23, 31, v22
	v_lshlrev_b64 v[22:23], 11, v[22:23]
	v_lshl_add_u64 v[22:23], v[30:31], 0, v[22:23]
	s_waitcnt lgkmcnt(0)
	global_store_dwordx4 v[22:23], v[26:29], off
	v_add_u32_e32 v22, 0x1400, v34
	s_nop 0
	v_ashrrev_i32_e32 v26, 5, v22
	v_mad_u64_u32 v[22:23], s[12:13], v26, s2, v[0:1]
	v_add_u32_e32 v26, s23, v26
	v_ashrrev_i32_e32 v27, 31, v26
	ds_read_b128 v[22:25], v22
	v_lshlrev_b64 v[26:27], 11, v[26:27]
	v_lshl_add_u64 v[32:33], v[30:31], 0, v[26:27]
	v_add_u32_e32 v26, 0x1600, v34
	v_ashrrev_i32_e32 v35, 5, v26
	v_mad_u64_u32 v[26:27], s[12:13], v35, s2, v[0:1]
	ds_read_b128 v[26:29], v26
	s_waitcnt lgkmcnt(1)
	global_store_dwordx4 v[32:33], v[22:25], off
	s_nop 1
	v_add_u32_e32 v22, s23, v35
	v_ashrrev_i32_e32 v23, 31, v22
	v_lshlrev_b64 v[22:23], 11, v[22:23]
	v_lshl_add_u64 v[22:23], v[30:31], 0, v[22:23]
	s_waitcnt lgkmcnt(0)
	global_store_dwordx4 v[22:23], v[26:29], off
	v_add_u32_e32 v22, 0x1800, v34
	s_nop 0
	v_ashrrev_i32_e32 v26, 5, v22
	v_mad_u64_u32 v[22:23], s[12:13], v26, s2, v[0:1]
	v_add_u32_e32 v26, s23, v26
	v_ashrrev_i32_e32 v27, 31, v26
	ds_read_b128 v[22:25], v22
	v_lshlrev_b64 v[26:27], 11, v[26:27]
	v_lshl_add_u64 v[32:33], v[30:31], 0, v[26:27]
	v_add_u32_e32 v26, 0x1a00, v34
	v_ashrrev_i32_e32 v35, 5, v26
	v_mad_u64_u32 v[26:27], s[12:13], v35, s2, v[0:1]
	ds_read_b128 v[26:29], v26
	s_waitcnt lgkmcnt(1)
	global_store_dwordx4 v[32:33], v[22:25], off
	s_nop 1
	v_add_u32_e32 v22, s23, v35
	v_ashrrev_i32_e32 v23, 31, v22
	v_lshlrev_b64 v[22:23], 11, v[22:23]
	v_lshl_add_u64 v[22:23], v[30:31], 0, v[22:23]
	s_waitcnt lgkmcnt(0)
	global_store_dwordx4 v[22:23], v[26:29], off
	v_add_u32_e32 v22, 0x1c00, v34
	s_nop 0
	v_ashrrev_i32_e32 v26, 5, v22
	v_mad_u64_u32 v[22:23], s[12:13], v26, s2, v[0:1]
	v_add_u32_e32 v26, s23, v26
	v_ashrrev_i32_e32 v27, 31, v26
	ds_read_b128 v[22:25], v22
	v_lshlrev_b64 v[26:27], 11, v[26:27]
	v_lshl_add_u64 v[32:33], v[30:31], 0, v[26:27]
	v_add_u32_e32 v26, 0x1e00, v34
	v_ashrrev_i32_e32 v34, 5, v26
	v_mad_u64_u32 v[26:27], s[12:13], v34, s2, v[0:1]
	ds_read_b128 v[26:29], v26
	s_waitcnt lgkmcnt(1)
	global_store_dwordx4 v[32:33], v[22:25], off
	s_mov_b64 s[12:13], -1
	s_nop 0
	v_add_u32_e32 v22, s23, v34
	v_ashrrev_i32_e32 v23, 31, v22
	v_lshlrev_b64 v[22:23], 11, v[22:23]
	v_lshl_add_u64 v[22:23], v[30:31], 0, v[22:23]
	s_waitcnt lgkmcnt(0)
	global_store_dwordx4 v[22:23], v[26:29], off
	s_barrier
	s_cbranch_vccz .LBB0_478
